# EpiResid phases: the last K-trip's ring re-stage loads now fetch the unit's residual tile by LDS-DMA (read back with ds_read in the epilogue) instead of a load round trip after the K loop
# speedup vs baseline: 1.0138x; 1.0021x over previous
.LBB0_429:
	s_add_i32 s96, s72, 2
	s_add_u32 s22, s70, 0x80
	s_addc_u32 s23, s71, 0
	s_add_i32 s67, 0, 0x10000
	s_cmp_eq_u32 s84, s72
	s_cselect_b32 s73, s9, s23
	s_cselect_b32 s72, s8, s22
	s_cselect_b32 s23, s69, s95
	s_cselect_b32 s22, s68, s48
	s_cselect_b32 s98, 1, 0
	s_add_i32 s97, 0, 0x14000
	v_add_u32_e32 v142, s67, v188
	v_add_u32_e32 v168, s97, v188
	ds_read_b128 v[130:133], v142
	ds_read_b128 v[134:137], v142 offset:1024
	ds_read_b128 v[138:141], v142 offset:2048
	ds_read_b128 v[142:145], v142 offset:3072
	ds_read_b128 v[146:149], v168
	ds_read_b128 v[150:153], v168 offset:1024
	ds_read_b128 v[154:157], v168 offset:2048
	ds_read_b128 v[168:171], v168 offset:3072
	v_lshl_add_u64 v[184:185], s[70:71], 0, v[166:167]
	s_add_i32 m0, s1, 0xc000
	ds_read_b128 v[172:175], v189
	ds_read_b128 v[176:179], v189 offset:1024
	ds_read_b128 v[180:183], v189 offset:2048
	ds_read_b128 v[190:193], v189 offset:3072
	ds_read_b128 v[194:197], v189 offset:4096
	ds_read_b128 v[198:201], v189 offset:5120
	ds_read_b128 v[202:205], v189 offset:6144
	ds_read_b128 v[206:209], v189 offset:7168
	global_load_lds_dwordx4 v[184:185], off
	v_lshl_add_u64 v[184:185], s[70:71], 0, v[164:165]
	s_add_i32 m0, s1, 0xe000
	s_nop 0
	global_load_lds_dwordx4 v[184:185], off
	s_waitcnt vmcnt(8)
	s_waitcnt lgkmcnt(0)
	s_barrier
	s_setprio 1
	s_waitcnt lgkmcnt(0)
	v_mfma_f32_16x16x32_bf16 v[126:129], v[130:133], v[172:175], v[126:129]
	v_mfma_f32_16x16x32_bf16 v[122:125], v[138:141], v[172:175], v[122:125]
	v_mfma_f32_16x16x32_bf16 v[110:113], v[130:133], v[180:183], v[110:113]
	v_mfma_f32_16x16x32_bf16 v[106:109], v[138:141], v[180:183], v[106:109]
	v_mfma_f32_16x16x32_bf16 v[92:95], v[130:133], v[194:197], v[92:95]
	v_mfma_f32_16x16x32_bf16 v[88:91], v[138:141], v[194:197], v[88:91]
	v_mfma_f32_16x16x32_bf16 v[76:79], v[130:133], v[202:205], v[76:79]
	v_mfma_f32_16x16x32_bf16 v[72:75], v[138:141], v[202:205], v[72:75]
	v_mfma_f32_16x16x32_bf16 v[126:129], v[134:137], v[176:179], v[126:129]
	v_mfma_f32_16x16x32_bf16 v[122:125], v[142:145], v[176:179], v[122:125]
	v_mfma_f32_16x16x32_bf16 v[110:113], v[134:137], v[190:193], v[110:113]
	v_mfma_f32_16x16x32_bf16 v[106:109], v[142:145], v[190:193], v[106:109]
	v_mfma_f32_16x16x32_bf16 v[92:95], v[134:137], v[198:201], v[92:95]
	v_mfma_f32_16x16x32_bf16 v[88:91], v[142:145], v[198:201], v[88:91]
	v_mfma_f32_16x16x32_bf16 v[76:79], v[134:137], v[206:209], v[76:79]
	v_mfma_f32_16x16x32_bf16 v[72:75], v[142:145], v[206:209], v[72:75]
	s_setprio 0
	s_setprio 1
	v_mfma_f32_16x16x32_bf16 v[118:121], v[146:149], v[172:175], v[118:121]
	v_mfma_f32_16x16x32_bf16 v[114:117], v[154:157], v[172:175], v[114:117]
	v_mfma_f32_16x16x32_bf16 v[102:105], v[146:149], v[180:183], v[102:105]
	v_mfma_f32_16x16x32_bf16 v[98:101], v[154:157], v[180:183], v[98:101]
	v_mfma_f32_16x16x32_bf16 v[84:87], v[146:149], v[194:197], v[84:87]
	v_mfma_f32_16x16x32_bf16 v[80:83], v[154:157], v[194:197], v[80:83]
	v_mfma_f32_16x16x32_bf16 v[68:71], v[146:149], v[202:205], v[68:71]
	v_mfma_f32_16x16x32_bf16 v[64:67], v[154:157], v[202:205], v[64:67]
	v_mfma_f32_16x16x32_bf16 v[118:121], v[150:153], v[176:179], v[118:121]
	v_mfma_f32_16x16x32_bf16 v[114:117], v[168:171], v[176:179], v[114:117]
	v_mfma_f32_16x16x32_bf16 v[102:105], v[150:153], v[190:193], v[102:105]
	v_mfma_f32_16x16x32_bf16 v[98:101], v[168:171], v[190:193], v[98:101]
	v_mfma_f32_16x16x32_bf16 v[84:87], v[150:153], v[198:201], v[84:87]
	v_mfma_f32_16x16x32_bf16 v[80:83], v[168:171], v[198:201], v[80:83]
	v_mfma_f32_16x16x32_bf16 v[68:71], v[150:153], v[206:209], v[68:71]
	v_mfma_f32_16x16x32_bf16 v[64:67], v[168:171], v[206:209], v[64:67]
	s_setprio 0
	s_barrier
	s_cmp_eq_u32 s98, 0
	s_cbranch_scc1 .Lresid_dma_skip0
	v_lshlrev_b32_e32 v96, 11, v187
	v_lshl_add_u32 v96, v186, 4, v96
	v_add_u32_e32 v162, 0x100, v96
	v_mov_b32_e32 v158, v96
	v_mov_b32_e32 v160, v162
	s_lshl_b32 s22, s35, 8
	s_add_i32 s22, s22, s80
	s_ashr_i32 s23, s22, 31
	s_lshl_b64 s[22:23], s[22:23], 11
	s_lshl_b32 s72, s44, 8
	s_or_b32 s72, s72, s81
	s_lshl_b32 s72, s72, 1
	s_add_u32 s22, s22, s72
	s_addc_u32 s23, s23, 0
	s_add_u32 s22, s22, s50
	s_addc_u32 s23, s23, s51
	s_add_u32 s72, s22, 0x10000
	s_addc_u32 s73, s23, 0
	s_mov_b32 s14, 0x8000
	s_mov_b32 s15, 0
	s_mov_b32 s56, 0x40000
	s_mov_b32 s57, 0
.Lresid_dma_skip0:
	s_add_i32 s67, s67, s66
	v_lshl_add_u64 v[184:185], s[22:23], 0, v[96:97]
	s_mov_b32 m0, s67
	ds_read_b128 v[172:175], v189 offset:16384
	ds_read_b128 v[176:179], v189 offset:17408
	ds_read_b128 v[180:183], v189 offset:18432
	ds_read_b128 v[190:193], v189 offset:19456
	ds_read_b128 v[194:197], v189 offset:20480
	ds_read_b128 v[198:201], v189 offset:21504
	ds_read_b128 v[202:205], v189 offset:22528
	ds_read_b128 v[206:209], v189 offset:23552
	global_load_lds_dwordx4 v[184:185], off
	s_add_i32 m0, s67, 0x2000
	v_lshl_add_u64 v[210:211], s[22:23], 0, v[162:163]
	s_add_u32 s22, s22, s14
	s_addc_u32 s23, s23, s15
	s_add_i32 s67, s97, s66
	global_load_lds_dwordx4 v[210:211], off
	v_lshl_add_u64 v[212:213], s[22:23], 0, v[96:97]
	s_mov_b32 m0, s67
	v_lshl_add_u64 v[214:215], s[22:23], 0, v[162:163]
	global_load_lds_dwordx4 v[212:213], off
	s_add_i32 m0, s67, 0x2000
	v_lshl_add_u64 v[216:217], s[72:73], 0, v[158:159]
	global_load_lds_dwordx4 v[214:215], off
	s_mov_b32 m0, s1
	v_lshl_add_u64 v[218:219], s[72:73], 0, v[160:161]
	global_load_lds_dwordx4 v[216:217], off
	s_mov_b32 m0, s75
	s_nop 0
	global_load_lds_dwordx4 v[218:219], off
	s_waitcnt vmcnt(8)
	s_waitcnt lgkmcnt(0)
	s_barrier
	s_setprio 1
	s_waitcnt lgkmcnt(0)
	v_mfma_f32_16x16x32_bf16 v[60:63], v[130:133], v[172:175], v[60:63]
	v_mfma_f32_16x16x32_bf16 v[56:59], v[138:141], v[172:175], v[56:59]
	v_mfma_f32_16x16x32_bf16 v[44:47], v[130:133], v[180:183], v[44:47]
	v_mfma_f32_16x16x32_bf16 v[40:43], v[138:141], v[180:183], v[40:43]
	v_mfma_f32_16x16x32_bf16 v[28:31], v[130:133], v[194:197], v[28:31]
	v_mfma_f32_16x16x32_bf16 v[24:27], v[138:141], v[194:197], v[24:27]
	v_mfma_f32_16x16x32_bf16 v[12:15], v[130:133], v[202:205], v[12:15]
	v_mfma_f32_16x16x32_bf16 v[8:11], v[138:141], v[202:205], v[8:11]
	v_mfma_f32_16x16x32_bf16 v[60:63], v[134:137], v[176:179], v[60:63]
	v_mfma_f32_16x16x32_bf16 v[56:59], v[142:145], v[176:179], v[56:59]
	v_mfma_f32_16x16x32_bf16 v[44:47], v[134:137], v[190:193], v[44:47]
	v_mfma_f32_16x16x32_bf16 v[40:43], v[142:145], v[190:193], v[40:43]
	v_mfma_f32_16x16x32_bf16 v[28:31], v[134:137], v[198:201], v[28:31]
	v_mfma_f32_16x16x32_bf16 v[24:27], v[142:145], v[198:201], v[24:27]
	v_mfma_f32_16x16x32_bf16 v[12:15], v[134:137], v[206:209], v[12:15]
	v_mfma_f32_16x16x32_bf16 v[8:11], v[142:145], v[206:209], v[8:11]
	s_setprio 0
	s_setprio 1
	v_mfma_f32_16x16x32_bf16 v[52:55], v[146:149], v[172:175], v[52:55]
	v_mfma_f32_16x16x32_bf16 v[48:51], v[154:157], v[172:175], v[48:51]
	v_mfma_f32_16x16x32_bf16 v[36:39], v[146:149], v[180:183], v[36:39]
	v_mfma_f32_16x16x32_bf16 v[32:35], v[154:157], v[180:183], v[32:35]
	v_mfma_f32_16x16x32_bf16 v[20:23], v[146:149], v[194:197], v[20:23]
	v_mfma_f32_16x16x32_bf16 v[16:19], v[154:157], v[194:197], v[16:19]
	v_mfma_f32_16x16x32_bf16 v[4:7], v[146:149], v[202:205], v[4:7]
	v_mfma_f32_16x16x32_bf16 v[0:3], v[154:157], v[202:205], v[0:3]
	v_mfma_f32_16x16x32_bf16 v[52:55], v[150:153], v[176:179], v[52:55]
	v_mfma_f32_16x16x32_bf16 v[48:51], v[168:171], v[176:179], v[48:51]
	v_mfma_f32_16x16x32_bf16 v[36:39], v[150:153], v[190:193], v[36:39]
	v_mfma_f32_16x16x32_bf16 v[32:35], v[168:171], v[190:193], v[32:35]
	v_mfma_f32_16x16x32_bf16 v[20:23], v[150:153], v[198:201], v[20:23]
	v_mfma_f32_16x16x32_bf16 v[16:19], v[168:171], v[198:201], v[16:19]
	v_mfma_f32_16x16x32_bf16 v[4:7], v[150:153], v[206:209], v[4:7]
	v_mfma_f32_16x16x32_bf16 v[0:3], v[168:171], v[206:209], v[0:3]
	s_setprio 0
	s_barrier
	s_add_i32 s67, 0, 0x18000
	s_add_i32 s97, 0, 0x1c000
	v_add_u32_e32 v142, s67, v188
	v_add_u32_e32 v168, s97, v188
	ds_read_b128 v[130:133], v142
	ds_read_b128 v[134:137], v142 offset:1024
	ds_read_b128 v[138:141], v142 offset:2048
	ds_read_b128 v[142:145], v142 offset:3072
	ds_read_b128 v[146:149], v168
	ds_read_b128 v[150:153], v168 offset:1024
	ds_read_b128 v[154:157], v168 offset:2048
	ds_read_b128 v[168:171], v168 offset:3072
	s_add_u32 s22, s72, s14
	s_addc_u32 s23, s73, s15
	s_mov_b32 m0, s76
	v_lshl_add_u64 v[236:237], s[22:23], 0, v[158:159]
	ds_read_b128 v[172:175], v189 offset:32768
	ds_read_b128 v[176:179], v189 offset:33792
	ds_read_b128 v[180:183], v189 offset:34816
	ds_read_b128 v[190:193], v189 offset:35840
	ds_read_b128 v[194:197], v189 offset:36864
	ds_read_b128 v[198:201], v189 offset:37888
	ds_read_b128 v[202:205], v189 offset:38912
	ds_read_b128 v[206:209], v189 offset:39936
	global_load_lds_dwordx4 v[236:237], off
	v_lshl_add_u64 v[236:237], s[22:23], 0, v[160:161]
	s_mov_b32 m0, s77
	s_nop 0
	global_load_lds_dwordx4 v[236:237], off
	s_waitcnt vmcnt(8)
	s_waitcnt lgkmcnt(0)
	s_barrier
	s_setprio 1
	s_waitcnt lgkmcnt(0)
	v_mfma_f32_16x16x32_bf16 v[126:129], v[130:133], v[172:175], v[126:129]
	v_mfma_f32_16x16x32_bf16 v[122:125], v[138:141], v[172:175], v[122:125]
	v_mfma_f32_16x16x32_bf16 v[110:113], v[130:133], v[180:183], v[110:113]
	v_mfma_f32_16x16x32_bf16 v[106:109], v[138:141], v[180:183], v[106:109]
	v_mfma_f32_16x16x32_bf16 v[92:95], v[130:133], v[194:197], v[92:95]
	v_mfma_f32_16x16x32_bf16 v[88:91], v[138:141], v[194:197], v[88:91]
	v_mfma_f32_16x16x32_bf16 v[76:79], v[130:133], v[202:205], v[76:79]
	v_mfma_f32_16x16x32_bf16 v[72:75], v[138:141], v[202:205], v[72:75]
	v_mfma_f32_16x16x32_bf16 v[126:129], v[134:137], v[176:179], v[126:129]
	v_mfma_f32_16x16x32_bf16 v[122:125], v[142:145], v[176:179], v[122:125]
	v_mfma_f32_16x16x32_bf16 v[110:113], v[134:137], v[190:193], v[110:113]
	v_mfma_f32_16x16x32_bf16 v[106:109], v[142:145], v[190:193], v[106:109]
	v_mfma_f32_16x16x32_bf16 v[92:95], v[134:137], v[198:201], v[92:95]
	v_mfma_f32_16x16x32_bf16 v[88:91], v[142:145], v[198:201], v[88:91]
	v_mfma_f32_16x16x32_bf16 v[76:79], v[134:137], v[206:209], v[76:79]
	v_mfma_f32_16x16x32_bf16 v[72:75], v[142:145], v[206:209], v[72:75]
	s_setprio 0
	s_setprio 1
	v_mfma_f32_16x16x32_bf16 v[118:121], v[146:149], v[172:175], v[118:121]
	v_mfma_f32_16x16x32_bf16 v[114:117], v[154:157], v[172:175], v[114:117]
	v_mfma_f32_16x16x32_bf16 v[102:105], v[146:149], v[180:183], v[102:105]
	v_mfma_f32_16x16x32_bf16 v[98:101], v[154:157], v[180:183], v[98:101]
	v_mfma_f32_16x16x32_bf16 v[84:87], v[146:149], v[194:197], v[84:87]
	v_mfma_f32_16x16x32_bf16 v[80:83], v[154:157], v[194:197], v[80:83]
	v_mfma_f32_16x16x32_bf16 v[68:71], v[146:149], v[202:205], v[68:71]
	v_mfma_f32_16x16x32_bf16 v[64:67], v[154:157], v[202:205], v[64:67]
	v_mfma_f32_16x16x32_bf16 v[118:121], v[150:153], v[176:179], v[118:121]
	v_mfma_f32_16x16x32_bf16 v[114:117], v[168:171], v[176:179], v[114:117]
	v_mfma_f32_16x16x32_bf16 v[102:105], v[150:153], v[190:193], v[102:105]
	v_mfma_f32_16x16x32_bf16 v[98:101], v[168:171], v[190:193], v[98:101]
	v_mfma_f32_16x16x32_bf16 v[84:87], v[150:153], v[198:201], v[84:87]
	v_mfma_f32_16x16x32_bf16 v[80:83], v[168:171], v[198:201], v[80:83]
	v_mfma_f32_16x16x32_bf16 v[68:71], v[150:153], v[206:209], v[68:71]
	v_mfma_f32_16x16x32_bf16 v[64:67], v[168:171], v[206:209], v[64:67]
	s_setprio 0
	s_barrier
	s_add_i32 s22, s67, s66
	v_lshl_add_u64 v[184:185], v[184:185], 0, s[56:57]
	s_mov_b32 m0, s22
	ds_read_b128 v[172:175], v189 offset:49152
	ds_read_b128 v[176:179], v189 offset:50176
	ds_read_b128 v[180:183], v189 offset:51200
	ds_read_b128 v[190:193], v189 offset:52224
	ds_read_b128 v[194:197], v189 offset:53248
	ds_read_b128 v[198:201], v189 offset:54272
	ds_read_b128 v[202:205], v189 offset:55296
	ds_read_b128 v[206:209], v189 offset:56320
	global_load_lds_dwordx4 v[184:185], off
	v_lshl_add_u64 v[184:185], v[210:211], 0, s[56:57]
	s_add_i32 m0, s22, 0x2000
	s_add_i32 s22, s97, s66
	global_load_lds_dwordx4 v[184:185], off
	v_lshl_add_u64 v[184:185], v[212:213], 0, s[56:57]
	s_mov_b32 m0, s22
	s_nop 0
	global_load_lds_dwordx4 v[184:185], off
	v_lshl_add_u64 v[184:185], v[214:215], 0, s[56:57]
	s_add_i32 m0, s22, 0x2000
	s_nop 0
	global_load_lds_dwordx4 v[184:185], off
	v_lshl_add_u64 v[184:185], v[216:217], 0, s[56:57]
	s_mov_b32 m0, s82
	s_nop 0
	global_load_lds_dwordx4 v[184:185], off
	v_lshl_add_u64 v[184:185], v[218:219], 0, s[56:57]
	s_mov_b32 m0, s83
	s_nop 0
	global_load_lds_dwordx4 v[184:185], off
	s_waitcnt vmcnt(8)
	s_waitcnt lgkmcnt(0)
	s_barrier
	s_setprio 1
	s_waitcnt lgkmcnt(0)
	v_mfma_f32_16x16x32_bf16 v[60:63], v[130:133], v[172:175], v[60:63]
	v_mfma_f32_16x16x32_bf16 v[56:59], v[138:141], v[172:175], v[56:59]
	v_mfma_f32_16x16x32_bf16 v[44:47], v[130:133], v[180:183], v[44:47]
	v_mfma_f32_16x16x32_bf16 v[40:43], v[138:141], v[180:183], v[40:43]
	v_mfma_f32_16x16x32_bf16 v[28:31], v[130:133], v[194:197], v[28:31]
	v_mfma_f32_16x16x32_bf16 v[24:27], v[138:141], v[194:197], v[24:27]
	v_mfma_f32_16x16x32_bf16 v[12:15], v[130:133], v[202:205], v[12:15]
	v_mfma_f32_16x16x32_bf16 v[8:11], v[138:141], v[202:205], v[8:11]
	v_mfma_f32_16x16x32_bf16 v[60:63], v[134:137], v[176:179], v[60:63]
	v_mfma_f32_16x16x32_bf16 v[56:59], v[142:145], v[176:179], v[56:59]
	v_mfma_f32_16x16x32_bf16 v[44:47], v[134:137], v[190:193], v[44:47]
	v_mfma_f32_16x16x32_bf16 v[40:43], v[142:145], v[190:193], v[40:43]
	v_mfma_f32_16x16x32_bf16 v[28:31], v[134:137], v[198:201], v[28:31]
	v_mfma_f32_16x16x32_bf16 v[24:27], v[142:145], v[198:201], v[24:27]
	v_mfma_f32_16x16x32_bf16 v[12:15], v[134:137], v[206:209], v[12:15]
	v_mfma_f32_16x16x32_bf16 v[8:11], v[142:145], v[206:209], v[8:11]
	s_setprio 0
	s_setprio 1
	v_mfma_f32_16x16x32_bf16 v[52:55], v[146:149], v[172:175], v[52:55]
	v_mfma_f32_16x16x32_bf16 v[48:51], v[154:157], v[172:175], v[48:51]
	v_mfma_f32_16x16x32_bf16 v[36:39], v[146:149], v[180:183], v[36:39]
	v_mfma_f32_16x16x32_bf16 v[32:35], v[154:157], v[180:183], v[32:35]
	v_mfma_f32_16x16x32_bf16 v[20:23], v[146:149], v[194:197], v[20:23]
	v_mfma_f32_16x16x32_bf16 v[16:19], v[154:157], v[194:197], v[16:19]
	v_mfma_f32_16x16x32_bf16 v[4:7], v[146:149], v[202:205], v[4:7]
	v_mfma_f32_16x16x32_bf16 v[0:3], v[154:157], v[202:205], v[0:3]
	v_mfma_f32_16x16x32_bf16 v[52:55], v[150:153], v[176:179], v[52:55]
	v_mfma_f32_16x16x32_bf16 v[48:51], v[168:171], v[176:179], v[48:51]
	v_mfma_f32_16x16x32_bf16 v[36:39], v[150:153], v[190:193], v[36:39]
	v_mfma_f32_16x16x32_bf16 v[32:35], v[168:171], v[190:193], v[32:35]
	v_mfma_f32_16x16x32_bf16 v[20:23], v[150:153], v[198:201], v[20:23]
	v_mfma_f32_16x16x32_bf16 v[16:19], v[168:171], v[198:201], v[16:19]
	v_mfma_f32_16x16x32_bf16 v[4:7], v[150:153], v[206:209], v[4:7]
	v_mfma_f32_16x16x32_bf16 v[0:3], v[168:171], v[206:209], v[0:3]
	s_setprio 0
	s_barrier
	s_add_u32 s48, s48, 0x100
	s_addc_u32 s95, s95, 0
	s_add_u32 s70, s70, 0x100
	s_addc_u32 s71, s71, 0
	s_cmp_ge_i32 s96, s79
	s_mov_b32 s72, s96
	s_cbranch_scc0 .LBB0_429

.LBB0_432:
	v_mov_b32_e32 v130, v187
	v_mov_b32_e32 v131, v186
	s_lshl_b32 s22, s35, 8
	s_add_i32 s22, s22, s80
	v_and_b32_e32 v132, 64, v225
	v_add_u32_e32 v170, s22, v130
	s_lshl_b32 s22, s44, 8
	v_xor_b32_e32 v130, 16, v225
	v_add_u32_e32 v132, 64, v132
	s_or_b32 s22, s22, s81
	v_cmp_lt_i32_e32 vcc, v130, v132
	v_lshl_add_u32 v168, v131, 3, s22
	v_ashrrev_i32_e32 v169, 31, v168
	v_cndmask_b32_e32 v130, v225, v130, vcc
	v_lshlrev_b32_e32 v190, 2, v130
	v_xor_b32_e32 v130, 32, v225
	v_cmp_lt_i32_e32 vcc, v130, v132
	v_lshlrev_b64 v[196:197], 1, v[168:169]
	v_ashrrev_i32_e32 v171, 31, v170
	v_cndmask_b32_e32 v130, v225, v130, vcc
	v_lshl_add_u64 v[172:173], s[50:51], 0, v[196:197]
	v_lshlrev_b64 v[198:199], 11, v[170:171]
	v_lshlrev_b32_e32 v191, 2, v130
	v_cmp_eq_u32_e32 vcc, 0, v131
	v_lshl_add_u64 v[130:131], v[172:173], 0, v[198:199]
	v_add_u32_e32 v182, 16, v170
	v_ashrrev_i32_e32 v183, 31, v182
	v_add_u32_e32 v178, 32, v170
	v_lshlrev_b64 v[184:185], 11, v[182:183]
	v_ashrrev_i32_e32 v179, 31, v178
	v_add_u32_e32 v174, 48, v170
	v_lshl_add_u64 v[130:131], v[172:173], 0, v[184:185]
	v_lshlrev_b64 v[180:181], 11, v[178:179]
	v_ashrrev_i32_e32 v175, 31, v174
	v_lshl_add_u64 v[130:131], v[172:173], 0, v[180:181]
	v_lshlrev_b64 v[176:177], 11, v[174:175]
	v_lshl_add_u64 v[130:131], v[172:173], 0, v[176:177]
	s_nop 0
	s_mov_b64 s[22:23], 0x40000
	v_lshl_add_u64 v[218:219], v[172:173], 0, v[198:199]
	v_lshl_add_u64 v[218:219], s[22:23], 0, v[218:219]
	v_lshl_add_u64 v[218:219], v[172:173], 0, v[184:185]
	v_lshl_add_u64 v[218:219], s[22:23], 0, v[218:219]
	v_lshl_add_u64 v[218:219], v[172:173], 0, v[180:181]
	v_lshl_add_u64 v[218:219], s[22:23], 0, v[218:219]
	v_lshl_add_u64 v[218:219], v[172:173], 0, v[176:177]
	v_lshl_add_u64 v[218:219], s[22:23], 0, v[218:219]
	global_load_dwordx4 v[244:247], v[218:219], off
	global_load_dwordx4 v[158:161], v[218:219], off offset:256
	s_mov_b64 s[56:57], 0x80
	s_waitcnt vmcnt(2)
	v_lshlrev_b32_e32 v200, 4, v220
	v_add_u32_e32 v201, 0x10000, v200
	ds_read_b128 v[192:195], v201
	ds_read_b128 v[154:157], v201 offset:8192
	ds_read_b128 v[150:153], v201 offset:16384
	ds_read_b128 v[146:149], v201 offset:24576
	ds_read_b128 v[142:145], v200
	ds_read_b128 v[138:141], v200 offset:8192
	ds_read_b128 v[134:137], v200 offset:16384
	ds_read_b128 v[130:133], v200 offset:24576
	ds_read_b128 v[202:205], v201 offset:32768
	ds_read_b128 v[206:209], v201 offset:40960
	ds_read_b128 v[210:213], v201 offset:49152
	ds_read_b128 v[214:217], v201 offset:57344
	ds_read_b128 v[236:239], v200 offset:32768
	ds_read_b128 v[240:243], v200 offset:40960
	s_waitcnt lgkmcnt(0)
	v_lshlrev_b32_e32 v200, 16, v192
	v_and_b32_e32 v201, 0xffff0000, v192
	v_lshlrev_b32_e32 v192, 16, v193
	v_and_b32_e32 v193, 0xffff0000, v193
	v_pk_fma_f32 v[128:129], v[128:129], 0.5, v[192:193] op_sel_hi:[1,0,1]
	v_lshlrev_b32_e32 v192, 16, v194
	v_and_b32_e32 v193, 0xffff0000, v194
	v_pk_fma_f32 v[126:127], v[126:127], 0.5, v[200:201] op_sel_hi:[1,0,1]
	v_pk_fma_f32 v[192:193], v[122:123], 0.5, v[192:193] op_sel_hi:[1,0,1]
	v_lshlrev_b32_e32 v122, 16, v195
	v_and_b32_e32 v123, 0xffff0000, v195
	v_pk_fma_f32 v[194:195], v[124:125], 0.5, v[122:123] op_sel_hi:[1,0,1]
	v_cvt_pk_bf16_f32 v122, v126, v127
	v_lshl_add_u64 v[126:127], s[50:51], 0, v[198:199]
	v_cvt_pk_bf16_f32 v123, v128, v129
	v_cvt_pk_bf16_f32 v124, v192, v193
	v_cvt_pk_bf16_f32 v125, v194, v195
	v_lshl_add_u64 v[126:127], v[126:127], 0, v[196:197]
	global_store_dwordx4 v[126:127], v[122:125], off
	v_lshlrev_b32_e32 v128, 16, v122
	v_lshlrev_b32_e32 v129, 16, v123
	v_and_b32_e32 v122, 0xffff0000, v122
	v_mul_f32_e32 v194, v122, v122
	v_fmac_f32_e32 v194, v128, v128
	v_and_b32_e32 v123, 0xffff0000, v123
	v_fmac_f32_e32 v194, v129, v129
	v_lshlrev_b32_e32 v192, 16, v124
	v_fmac_f32_e32 v194, v123, v123
	v_lshlrev_b32_e32 v122, 16, v154
	v_and_b32_e32 v123, 0xffff0000, v154
	v_and_b32_e32 v124, 0xffff0000, v124
	v_fmac_f32_e32 v194, v192, v192
	v_pk_fma_f32 v[118:119], v[118:119], 0.5, v[122:123] op_sel_hi:[1,0,1]
	v_lshlrev_b32_e32 v122, 16, v155
	v_and_b32_e32 v123, 0xffff0000, v155
	v_lshlrev_b32_e32 v193, 16, v125
	v_fmac_f32_e32 v194, v124, v124
	v_pk_fma_f32 v[120:121], v[120:121], 0.5, v[122:123] op_sel_hi:[1,0,1]
	v_lshlrev_b32_e32 v122, 16, v156
	v_and_b32_e32 v123, 0xffff0000, v156
	v_and_b32_e32 v125, 0xffff0000, v125
	v_fmac_f32_e32 v194, v193, v193
	v_pk_fma_f32 v[122:123], v[114:115], 0.5, v[122:123] op_sel_hi:[1,0,1]
	v_lshlrev_b32_e32 v114, 16, v157
	v_and_b32_e32 v115, 0xffff0000, v157
	v_fmac_f32_e32 v194, v125, v125
	v_pk_fma_f32 v[124:125], v[116:117], 0.5, v[114:115] op_sel_hi:[1,0,1]
	v_cvt_pk_bf16_f32 v114, v118, v119
	v_cvt_pk_bf16_f32 v115, v120, v121
	v_cvt_pk_bf16_f32 v116, v122, v123
	v_cvt_pk_bf16_f32 v117, v124, v125
	v_lshlrev_b32_e32 v118, 16, v114
	global_store_dwordx4 v[126:127], v[114:117], off offset:256
	v_fmac_f32_e32 v194, v118, v118
	v_lshlrev_b32_e32 v119, 16, v115
	v_and_b32_e32 v114, 0xffff0000, v114
	v_fmac_f32_e32 v194, v114, v114
	v_and_b32_e32 v115, 0xffff0000, v115
	v_fmac_f32_e32 v194, v119, v119
	v_lshlrev_b32_e32 v120, 16, v116
	v_fmac_f32_e32 v194, v115, v115
	v_and_b32_e32 v116, 0xffff0000, v116
	v_fmac_f32_e32 v194, v120, v120
	v_lshlrev_b32_e32 v121, 16, v117
	v_fmac_f32_e32 v194, v116, v116
	v_and_b32_e32 v117, 0xffff0000, v117
	v_fmac_f32_e32 v194, v121, v121
	v_fmac_f32_e32 v194, v117, v117
	ds_bpermute_b32 v114, v190, v194
	s_waitcnt lgkmcnt(0)
	v_add_f32_e32 v114, v194, v114
	ds_bpermute_b32 v115, v191, v114
	s_and_saveexec_b64 s[70:71], vcc
	s_cbranch_execz .LBB0_434
	s_waitcnt lgkmcnt(0)
	v_add_f32_e32 v116, v114, v115
	s_lshl_b32 s22, s44, 2
	v_lshlrev_b64 v[114:115], 6, v[170:171]
	s_ashr_i32 s23, s22, 31
	v_lshl_add_u64 v[114:115], s[52:53], 0, v[114:115]
	v_lshl_add_u64 v[114:115], s[22:23], 2, v[114:115]
	s_lshl_b32 s48, s78, 2
	v_lshl_add_u64 v[114:115], v[114:115], 0, s[48:49]
	global_store_dword v[114:115], v116, off

.LBB0_440:
	s_or_b64 exec, exec, s[70:71]
	v_add_u32_e32 v106, 0x80, v170
	v_ashrrev_i32_e32 v107, 31, v106
	v_lshlrev_b64 v[112:113], 11, v[106:107]
	s_waitcnt lgkmcnt(0)
	v_lshl_add_u64 v[64:65], v[172:173], 0, v[112:113]
	v_mov_b32_e32 v108, v202
	v_mov_b32_e32 v109, v203
	v_mov_b32_e32 v110, v204
	v_mov_b32_e32 v111, v205
	v_mov_b32_e32 v88, v206
	v_mov_b32_e32 v89, v207
	v_mov_b32_e32 v90, v208
	v_mov_b32_e32 v91, v209
	v_add_u32_e32 v102, 0x90, v170
	v_ashrrev_i32_e32 v103, 31, v102
	v_add_u32_e32 v98, 0xa0, v170
	v_lshlrev_b64 v[104:105], 11, v[102:103]
	v_ashrrev_i32_e32 v99, 31, v98
	v_add_u32_e32 v92, 0xb0, v170
	v_lshl_add_u64 v[64:65], v[172:173], 0, v[104:105]
	v_lshlrev_b64 v[100:101], 11, v[98:99]
	v_ashrrev_i32_e32 v93, 31, v92
	v_mov_b32_e32 v84, v210
	v_mov_b32_e32 v85, v211
	v_mov_b32_e32 v86, v212
	v_mov_b32_e32 v87, v213
	v_mov_b32_e32 v80, v214
	v_mov_b32_e32 v81, v215
	v_mov_b32_e32 v82, v216
	v_mov_b32_e32 v83, v217
	v_lshl_add_u64 v[64:65], v[172:173], 0, v[100:101]
	v_lshlrev_b64 v[94:95], 11, v[92:93]
	v_mov_b32_e32 v76, v236
	v_mov_b32_e32 v77, v237
	v_mov_b32_e32 v78, v238
	v_mov_b32_e32 v79, v239
	v_mov_b32_e32 v72, v240
	v_mov_b32_e32 v73, v241
	v_mov_b32_e32 v74, v242
	v_mov_b32_e32 v75, v243
	v_lshl_add_u64 v[64:65], v[172:173], 0, v[94:95]
	s_waitcnt vmcnt(8)
	v_mov_b32_e32 v68, v244
	v_mov_b32_e32 v69, v245
	v_mov_b32_e32 v70, v246
	v_mov_b32_e32 v71, v247
	s_nop 0
	v_mov_b32_e32 v64, v158
	v_mov_b32_e32 v65, v159
	v_mov_b32_e32 v66, v160
	v_mov_b32_e32 v67, v161
	v_lshlrev_b32_e32 v114, 16, v108
	v_and_b32_e32 v115, 0xffff0000, v108
	v_lshlrev_b32_e32 v108, 16, v109
	v_and_b32_e32 v109, 0xffff0000, v109
	v_pk_fma_f32 v[62:63], v[62:63], 0.5, v[108:109] op_sel_hi:[1,0,1]
	v_lshlrev_b32_e32 v108, 16, v110
	v_and_b32_e32 v109, 0xffff0000, v110
	v_pk_fma_f32 v[60:61], v[60:61], 0.5, v[114:115] op_sel_hi:[1,0,1]
	v_pk_fma_f32 v[108:109], v[56:57], 0.5, v[108:109] op_sel_hi:[1,0,1]
	v_lshlrev_b32_e32 v56, 16, v111
	v_and_b32_e32 v57, 0xffff0000, v111
	v_pk_fma_f32 v[110:111], v[58:59], 0.5, v[56:57] op_sel_hi:[1,0,1]
	v_cvt_pk_bf16_f32 v56, v60, v61
	v_lshl_add_u64 v[60:61], s[50:51], 0, v[112:113]
	v_cvt_pk_bf16_f32 v57, v62, v63
	v_cvt_pk_bf16_f32 v58, v108, v109
	v_cvt_pk_bf16_f32 v59, v110, v111
	v_lshl_add_u64 v[60:61], v[168:169], 1, v[60:61]
	global_store_dwordx4 v[60:61], v[56:59], off
	v_lshlrev_b32_e32 v62, 16, v56
	v_lshlrev_b32_e32 v63, 16, v57
	v_and_b32_e32 v56, 0xffff0000, v56
	v_mul_f32_e32 v110, v56, v56
	v_fmac_f32_e32 v110, v62, v62
	v_and_b32_e32 v57, 0xffff0000, v57
	v_fmac_f32_e32 v110, v63, v63
	v_lshlrev_b32_e32 v108, 16, v58
	v_fmac_f32_e32 v110, v57, v57
	v_lshlrev_b32_e32 v56, 16, v88
	v_and_b32_e32 v57, 0xffff0000, v88
	v_and_b32_e32 v58, 0xffff0000, v58
	v_fmac_f32_e32 v110, v108, v108
	v_pk_fma_f32 v[52:53], v[52:53], 0.5, v[56:57] op_sel_hi:[1,0,1]
	v_lshlrev_b32_e32 v56, 16, v89
	v_and_b32_e32 v57, 0xffff0000, v89
	v_lshlrev_b32_e32 v109, 16, v59
	v_fmac_f32_e32 v110, v58, v58
	v_pk_fma_f32 v[54:55], v[54:55], 0.5, v[56:57] op_sel_hi:[1,0,1]
	v_lshlrev_b32_e32 v56, 16, v90
	v_and_b32_e32 v57, 0xffff0000, v90
	v_and_b32_e32 v59, 0xffff0000, v59
	v_fmac_f32_e32 v110, v109, v109
	v_pk_fma_f32 v[56:57], v[48:49], 0.5, v[56:57] op_sel_hi:[1,0,1]
	v_lshlrev_b32_e32 v48, 16, v91
	v_and_b32_e32 v49, 0xffff0000, v91
	v_fmac_f32_e32 v110, v59, v59
	v_pk_fma_f32 v[58:59], v[50:51], 0.5, v[48:49] op_sel_hi:[1,0,1]
	v_cvt_pk_bf16_f32 v48, v52, v53
	v_cvt_pk_bf16_f32 v49, v54, v55
	v_cvt_pk_bf16_f32 v50, v56, v57
	v_cvt_pk_bf16_f32 v51, v58, v59
	v_lshlrev_b32_e32 v52, 16, v48
	global_store_dwordx4 v[60:61], v[48:51], off offset:256
	v_fmac_f32_e32 v110, v52, v52
	v_lshlrev_b32_e32 v53, 16, v49
	v_and_b32_e32 v48, 0xffff0000, v48
	v_fmac_f32_e32 v110, v48, v48
	v_and_b32_e32 v49, 0xffff0000, v49
	v_fmac_f32_e32 v110, v53, v53
	v_lshlrev_b32_e32 v54, 16, v50
	v_fmac_f32_e32 v110, v49, v49
	v_and_b32_e32 v50, 0xffff0000, v50
	v_fmac_f32_e32 v110, v54, v54
	v_lshlrev_b32_e32 v55, 16, v51
	v_fmac_f32_e32 v110, v50, v50
	v_and_b32_e32 v51, 0xffff0000, v51
	v_fmac_f32_e32 v110, v55, v55
	v_fmac_f32_e32 v110, v51, v51
	ds_bpermute_b32 v48, v190, v110
	s_waitcnt lgkmcnt(0)
	v_add_f32_e32 v48, v110, v48
	ds_bpermute_b32 v49, v191, v48
	s_and_saveexec_b64 s[70:71], vcc
	s_cbranch_execz .LBB0_442
	s_waitcnt lgkmcnt(0)
	v_add_f32_e32 v50, v48, v49
	s_lshl_b32 s22, s44, 2
	v_lshlrev_b64 v[48:49], 6, v[106:107]
	s_ashr_i32 s23, s22, 31
	v_lshl_add_u64 v[48:49], s[52:53], 0, v[48:49]
	v_lshl_add_u64 v[48:49], s[22:23], 2, v[48:49]
	s_lshl_b32 s48, s78, 2
	v_lshl_add_u64 v[48:49], v[48:49], 0, s[48:49]
	global_store_dword v[48:49], v50, off

.LBB0_1828:
	v_mov_b32_e32 v130, v186
	v_mov_b32_e32 v131, v187
	s_lshl_b32 s22, s35, 8
	s_add_i32 s22, s22, s80
	v_and_b32_e32 v132, 64, v225
	v_add_u32_e32 v170, s22, v131
	s_lshl_b32 s22, s44, 8
	v_xor_b32_e32 v131, 16, v225
	v_add_u32_e32 v132, 64, v132
	s_or_b32 s22, s22, s81
	v_cmp_lt_i32_e32 vcc, v131, v132
	v_lshl_add_u32 v168, v130, 3, s22
	v_ashrrev_i32_e32 v169, 31, v168
	v_cndmask_b32_e32 v131, v225, v131, vcc
	v_lshlrev_b32_e32 v190, 2, v131
	v_xor_b32_e32 v131, 32, v225
	v_cmp_lt_i32_e32 vcc, v131, v132
	v_lshlrev_b64 v[196:197], 1, v[168:169]
	v_ashrrev_i32_e32 v171, 31, v170
	v_cndmask_b32_e32 v131, v225, v131, vcc
	v_lshl_add_u64 v[172:173], s[50:51], 0, v[196:197]
	v_lshlrev_b64 v[198:199], 11, v[170:171]
	v_lshlrev_b32_e32 v191, 2, v131
	v_cmp_eq_u32_e32 vcc, 0, v130
	v_lshl_add_u64 v[130:131], v[172:173], 0, v[198:199]
	v_add_u32_e32 v182, 16, v170
	v_ashrrev_i32_e32 v183, 31, v182
	v_add_u32_e32 v178, 32, v170
	v_lshlrev_b64 v[184:185], 11, v[182:183]
	v_ashrrev_i32_e32 v179, 31, v178
	v_add_u32_e32 v174, 48, v170
	v_lshl_add_u64 v[130:131], v[172:173], 0, v[184:185]
	v_lshlrev_b64 v[180:181], 11, v[178:179]
	v_ashrrev_i32_e32 v175, 31, v174
	v_lshl_add_u64 v[130:131], v[172:173], 0, v[180:181]
	v_lshlrev_b64 v[176:177], 11, v[174:175]
	v_lshl_add_u64 v[130:131], v[172:173], 0, v[176:177]
	s_nop 0
	s_mov_b64 s[22:23], 0x40000
	v_lshl_add_u64 v[218:219], v[172:173], 0, v[198:199]
	v_lshl_add_u64 v[218:219], s[22:23], 0, v[218:219]
	v_lshl_add_u64 v[218:219], v[172:173], 0, v[184:185]
	v_lshl_add_u64 v[218:219], s[22:23], 0, v[218:219]
	v_lshl_add_u64 v[218:219], v[172:173], 0, v[180:181]
	v_lshl_add_u64 v[218:219], s[22:23], 0, v[218:219]
	v_lshl_add_u64 v[218:219], v[172:173], 0, v[176:177]
	v_lshl_add_u64 v[218:219], s[22:23], 0, v[218:219]
	global_load_dwordx4 v[244:247], v[218:219], off
	global_load_dwordx4 v[158:161], v[218:219], off offset:256
	s_mov_b64 s[56:57], 0x80
	s_waitcnt vmcnt(2)
	v_lshlrev_b32_e32 v200, 4, v220
	v_add_u32_e32 v201, 0x10000, v200
	ds_read_b128 v[192:195], v201
	ds_read_b128 v[154:157], v201 offset:8192
	ds_read_b128 v[150:153], v201 offset:16384
	ds_read_b128 v[146:149], v201 offset:24576
	ds_read_b128 v[142:145], v200
	ds_read_b128 v[138:141], v200 offset:8192
	ds_read_b128 v[134:137], v200 offset:16384
	ds_read_b128 v[130:133], v200 offset:24576
	ds_read_b128 v[202:205], v201 offset:32768
	ds_read_b128 v[206:209], v201 offset:40960
	ds_read_b128 v[210:213], v201 offset:49152
	ds_read_b128 v[214:217], v201 offset:57344
	ds_read_b128 v[236:239], v200 offset:32768
	ds_read_b128 v[240:243], v200 offset:40960
	s_waitcnt lgkmcnt(0)
	v_lshlrev_b32_e32 v200, 16, v192
	v_and_b32_e32 v201, 0xffff0000, v192
	v_lshlrev_b32_e32 v192, 16, v193
	v_and_b32_e32 v193, 0xffff0000, v193
	v_pk_add_f32 v[128:129], v[128:129], v[192:193]
	v_lshlrev_b32_e32 v192, 16, v194
	v_and_b32_e32 v193, 0xffff0000, v194
	v_pk_add_f32 v[126:127], v[126:127], v[200:201]
	v_pk_add_f32 v[192:193], v[122:123], v[192:193]
	v_lshlrev_b32_e32 v122, 16, v195
	v_and_b32_e32 v123, 0xffff0000, v195
	v_pk_add_f32 v[194:195], v[124:125], v[122:123]
	v_cvt_pk_bf16_f32 v122, v126, v127
	v_lshl_add_u64 v[126:127], s[50:51], 0, v[198:199]
	v_cvt_pk_bf16_f32 v123, v128, v129
	v_cvt_pk_bf16_f32 v124, v192, v193
	v_cvt_pk_bf16_f32 v125, v194, v195
	v_lshl_add_u64 v[126:127], v[126:127], 0, v[196:197]
	global_store_dwordx4 v[126:127], v[122:125], off
	v_lshlrev_b32_e32 v128, 16, v122
	v_lshlrev_b32_e32 v129, 16, v123
	v_and_b32_e32 v122, 0xffff0000, v122
	v_mul_f32_e32 v194, v122, v122
	v_fmac_f32_e32 v194, v128, v128
	v_and_b32_e32 v123, 0xffff0000, v123
	v_fmac_f32_e32 v194, v129, v129
	v_lshlrev_b32_e32 v192, 16, v124
	v_fmac_f32_e32 v194, v123, v123
	v_lshlrev_b32_e32 v122, 16, v154
	v_and_b32_e32 v123, 0xffff0000, v154
	v_and_b32_e32 v124, 0xffff0000, v124
	v_fmac_f32_e32 v194, v192, v192
	v_pk_add_f32 v[118:119], v[118:119], v[122:123]
	v_lshlrev_b32_e32 v122, 16, v155
	v_and_b32_e32 v123, 0xffff0000, v155
	v_lshlrev_b32_e32 v193, 16, v125
	v_fmac_f32_e32 v194, v124, v124
	v_pk_add_f32 v[120:121], v[120:121], v[122:123]
	v_lshlrev_b32_e32 v122, 16, v156
	v_and_b32_e32 v123, 0xffff0000, v156
	v_and_b32_e32 v125, 0xffff0000, v125
	v_fmac_f32_e32 v194, v193, v193
	v_pk_add_f32 v[122:123], v[114:115], v[122:123]
	v_lshlrev_b32_e32 v114, 16, v157
	v_and_b32_e32 v115, 0xffff0000, v157
	v_fmac_f32_e32 v194, v125, v125
	v_pk_add_f32 v[124:125], v[116:117], v[114:115]
	v_cvt_pk_bf16_f32 v114, v118, v119
	v_cvt_pk_bf16_f32 v115, v120, v121
	v_cvt_pk_bf16_f32 v116, v122, v123
	v_cvt_pk_bf16_f32 v117, v124, v125
	v_lshlrev_b32_e32 v118, 16, v114
	global_store_dwordx4 v[126:127], v[114:117], off offset:256
	v_fmac_f32_e32 v194, v118, v118
	v_lshlrev_b32_e32 v119, 16, v115
	v_and_b32_e32 v114, 0xffff0000, v114
	v_fmac_f32_e32 v194, v114, v114
	v_and_b32_e32 v115, 0xffff0000, v115
	v_fmac_f32_e32 v194, v119, v119
	v_lshlrev_b32_e32 v120, 16, v116
	v_fmac_f32_e32 v194, v115, v115
	v_and_b32_e32 v116, 0xffff0000, v116
	v_fmac_f32_e32 v194, v120, v120
	v_lshlrev_b32_e32 v121, 16, v117
	v_fmac_f32_e32 v194, v116, v116
	v_and_b32_e32 v117, 0xffff0000, v117
	v_fmac_f32_e32 v194, v121, v121
	v_fmac_f32_e32 v194, v117, v117
	ds_bpermute_b32 v114, v190, v194
	s_waitcnt lgkmcnt(0)
	v_add_f32_e32 v114, v194, v114
	ds_bpermute_b32 v115, v191, v114
	s_and_saveexec_b64 s[70:71], vcc
	s_cbranch_execz .LBB0_1830
	s_waitcnt lgkmcnt(0)
	v_add_f32_e32 v116, v114, v115
	s_lshl_b32 s22, s44, 2
	v_lshlrev_b64 v[114:115], 6, v[170:171]
	s_ashr_i32 s23, s22, 31
	v_lshl_add_u64 v[114:115], s[52:53], 0, v[114:115]
	v_lshl_add_u64 v[114:115], s[22:23], 2, v[114:115]
	s_lshl_b32 s48, s78, 2
	v_lshl_add_u64 v[114:115], v[114:115], 0, s[48:49]
	global_store_dword v[114:115], v116, off

.LBB0_1836:
	s_or_b64 exec, exec, s[70:71]
	v_add_u32_e32 v106, 0x80, v170
	v_ashrrev_i32_e32 v107, 31, v106
	v_lshlrev_b64 v[112:113], 11, v[106:107]
	s_waitcnt lgkmcnt(0)
	v_lshl_add_u64 v[64:65], v[172:173], 0, v[112:113]
	v_mov_b32_e32 v108, v202
	v_mov_b32_e32 v109, v203
	v_mov_b32_e32 v110, v204
	v_mov_b32_e32 v111, v205
	v_mov_b32_e32 v88, v206
	v_mov_b32_e32 v89, v207
	v_mov_b32_e32 v90, v208
	v_mov_b32_e32 v91, v209
	v_add_u32_e32 v102, 0x90, v170
	v_ashrrev_i32_e32 v103, 31, v102
	v_add_u32_e32 v98, 0xa0, v170
	v_lshlrev_b64 v[104:105], 11, v[102:103]
	v_ashrrev_i32_e32 v99, 31, v98
	v_add_u32_e32 v92, 0xb0, v170
	v_lshl_add_u64 v[64:65], v[172:173], 0, v[104:105]
	v_lshlrev_b64 v[100:101], 11, v[98:99]
	v_ashrrev_i32_e32 v93, 31, v92
	v_mov_b32_e32 v84, v210
	v_mov_b32_e32 v85, v211
	v_mov_b32_e32 v86, v212
	v_mov_b32_e32 v87, v213
	v_mov_b32_e32 v80, v214
	v_mov_b32_e32 v81, v215
	v_mov_b32_e32 v82, v216
	v_mov_b32_e32 v83, v217
	v_lshl_add_u64 v[64:65], v[172:173], 0, v[100:101]
	v_lshlrev_b64 v[94:95], 11, v[92:93]
	v_mov_b32_e32 v76, v236
	v_mov_b32_e32 v77, v237
	v_mov_b32_e32 v78, v238
	v_mov_b32_e32 v79, v239
	v_mov_b32_e32 v72, v240
	v_mov_b32_e32 v73, v241
	v_mov_b32_e32 v74, v242
	v_mov_b32_e32 v75, v243
	v_lshl_add_u64 v[64:65], v[172:173], 0, v[94:95]
	s_waitcnt vmcnt(8)
	v_mov_b32_e32 v68, v244
	v_mov_b32_e32 v69, v245
	v_mov_b32_e32 v70, v246
	v_mov_b32_e32 v71, v247
	s_nop 0
	v_mov_b32_e32 v64, v158
	v_mov_b32_e32 v65, v159
	v_mov_b32_e32 v66, v160
	v_mov_b32_e32 v67, v161
	v_lshlrev_b32_e32 v114, 16, v108
	v_and_b32_e32 v115, 0xffff0000, v108
	v_lshlrev_b32_e32 v108, 16, v109
	v_and_b32_e32 v109, 0xffff0000, v109
	v_pk_add_f32 v[62:63], v[62:63], v[108:109]
	v_lshlrev_b32_e32 v108, 16, v110
	v_and_b32_e32 v109, 0xffff0000, v110
	v_pk_add_f32 v[60:61], v[60:61], v[114:115]
	v_pk_add_f32 v[108:109], v[56:57], v[108:109]
	v_lshlrev_b32_e32 v56, 16, v111
	v_and_b32_e32 v57, 0xffff0000, v111
	v_pk_add_f32 v[110:111], v[58:59], v[56:57]
	v_cvt_pk_bf16_f32 v56, v60, v61
	v_lshl_add_u64 v[60:61], s[50:51], 0, v[112:113]
	v_cvt_pk_bf16_f32 v57, v62, v63
	v_cvt_pk_bf16_f32 v58, v108, v109
	v_cvt_pk_bf16_f32 v59, v110, v111
	v_lshl_add_u64 v[60:61], v[168:169], 1, v[60:61]
	global_store_dwordx4 v[60:61], v[56:59], off
	v_lshlrev_b32_e32 v62, 16, v56
	v_lshlrev_b32_e32 v63, 16, v57
	v_and_b32_e32 v56, 0xffff0000, v56
	v_mul_f32_e32 v110, v56, v56
	v_fmac_f32_e32 v110, v62, v62
	v_and_b32_e32 v57, 0xffff0000, v57
	v_fmac_f32_e32 v110, v63, v63
	v_lshlrev_b32_e32 v108, 16, v58
	v_fmac_f32_e32 v110, v57, v57
	v_lshlrev_b32_e32 v56, 16, v88
	v_and_b32_e32 v57, 0xffff0000, v88
	v_and_b32_e32 v58, 0xffff0000, v58
	v_fmac_f32_e32 v110, v108, v108
	v_pk_add_f32 v[52:53], v[52:53], v[56:57]
	v_lshlrev_b32_e32 v56, 16, v89
	v_and_b32_e32 v57, 0xffff0000, v89
	v_lshlrev_b32_e32 v109, 16, v59
	v_fmac_f32_e32 v110, v58, v58
	v_pk_add_f32 v[54:55], v[54:55], v[56:57]
	v_lshlrev_b32_e32 v56, 16, v90
	v_and_b32_e32 v57, 0xffff0000, v90
	v_and_b32_e32 v59, 0xffff0000, v59
	v_fmac_f32_e32 v110, v109, v109
	v_pk_add_f32 v[56:57], v[48:49], v[56:57]
	v_lshlrev_b32_e32 v48, 16, v91
	v_and_b32_e32 v49, 0xffff0000, v91
	v_fmac_f32_e32 v110, v59, v59
	v_pk_add_f32 v[58:59], v[50:51], v[48:49]
	v_cvt_pk_bf16_f32 v48, v52, v53
	v_cvt_pk_bf16_f32 v49, v54, v55
	v_cvt_pk_bf16_f32 v50, v56, v57
	v_cvt_pk_bf16_f32 v51, v58, v59
	v_lshlrev_b32_e32 v52, 16, v48
	global_store_dwordx4 v[60:61], v[48:51], off offset:256
	v_fmac_f32_e32 v110, v52, v52
	v_lshlrev_b32_e32 v53, 16, v49
	v_and_b32_e32 v48, 0xffff0000, v48
	v_fmac_f32_e32 v110, v48, v48
	v_and_b32_e32 v49, 0xffff0000, v49
	v_fmac_f32_e32 v110, v53, v53
	v_lshlrev_b32_e32 v54, 16, v50
	v_fmac_f32_e32 v110, v49, v49
	v_and_b32_e32 v50, 0xffff0000, v50
	v_fmac_f32_e32 v110, v54, v54
	v_lshlrev_b32_e32 v55, 16, v51
	v_fmac_f32_e32 v110, v50, v50
	v_and_b32_e32 v51, 0xffff0000, v51
	v_fmac_f32_e32 v110, v55, v55
	v_fmac_f32_e32 v110, v51, v51
	ds_bpermute_b32 v48, v190, v110
	s_waitcnt lgkmcnt(0)
	v_add_f32_e32 v48, v110, v48
	ds_bpermute_b32 v49, v191, v48
	s_and_saveexec_b64 s[70:71], vcc
	s_cbranch_execz .LBB0_1838
	s_waitcnt lgkmcnt(0)
	v_add_f32_e32 v50, v48, v49
	s_lshl_b32 s22, s44, 2
	v_lshlrev_b64 v[48:49], 6, v[106:107]
	s_ashr_i32 s23, s22, 31
	v_lshl_add_u64 v[48:49], s[52:53], 0, v[48:49]
	v_lshl_add_u64 v[48:49], s[22:23], 2, v[48:49]
	s_lshl_b32 s48, s78, 2
	v_lshl_add_u64 v[48:49], v[48:49], 0, s[48:49]
	global_store_dword v[48:49], v50, off
